# up-GEMM k-loop: in the two phases whose last-read LDS buffers are not restaged in the following interval, wait lgkmcnt(4) before the barrier and lgkmcnt(0) after the 4th MFMA (waits moved to first con
# baseline (speedup 1.0000x reference)
; #define PG8_STAGE(bufoff, gbase, voff) do { _Pragma("unroll") for (int _i = 0; _i < 2; ++_i) \
;         __builtin_amdgcn_global_load_lds((const unsigned*)((const char*)(gbase) + (voff)[_i]), (LAS unsigned*)(lds + (bufoff) + ldsw + _i * 8192), 16, 0, 0); } while (0)
; #define PG8_LDA(dst, b, h) do { _Pragma("unroll") for (int m = 0; m < 4; ++m) _Pragma("unroll") for (int k = 0; k < 2; ++k) dst[m][k] = *(const LAS bf16x8*)(lds + PG8_SA(b, h) + aoff + m * 2048 + k * 1024); } while (0)
; #define PG8_LDB(dst, b, h) do { _Pragma("unroll") for (int n = 0; n < 2; ++n) _Pragma("unroll") for (int k = 0; k < 2; ++k) dst[n][k] = *(const LAS bf16x8*)(lds + PG8_SB(b, h) + boff + n * 2048 + k * 1024); } while (0)
; #define PG8_MMA(ai, bj, At, Bt) do { __builtin_amdgcn_s_setprio(1); _Pragma("unroll") for (int m = 0; m < 4; ++m) _Pragma("unroll") for (int n = 0; n < 2; ++n) _Pragma("unroll") for (int k = 0; k < 2; ++k) \
;         acc[ai][bj][m][n] = __builtin_amdgcn_mfma_f32_16x16x32_bf16(Bt[n][k], At[m][k], acc[ai][bj][m][n], 0, 0, 0); __builtin_amdgcn_s_setprio(0); } while (0)
; #define PG8_WAIT_V(n) asm volatile("s_waitcnt vmcnt(" #n ")" ::: "memory")
; #define PG8_WAIT_L(n) asm volatile("s_waitcnt lgkmcnt(" #n ")" ::: "memory")
; #define PG8_BAR __builtin_amdgcn_s_barrier()
; template <class Epi, class Sched, bool ALIGN_EPI = false, bool SP2 = false>
; __device__ __forceinline__ void gemm_phase(LAS unsigned char* lds, const Gemm g, const Sched& S, const Epi& E, int wid) {
;     ...
;         for (int t = 0; t < nt; t += 2) {
;             const bool last = (t == nt - 2);
;             const char* a1 = cA + (size_t)(t + 1) * kstep;
;             const char* a2 = last ? nA : cA + (size_t)(t + 2) * kstep; const char* b2 = last ? nB : cB + (size_t)(t + 2) * kstep;
;             const char* a3 = a2 + kstep; const char* b3 = b2 + kstep;
;             if constexpr (SP2) {
;             PG8_LDB(B0, 0, 0); PG8_LDB(B1, 0, 1); PG8_SCHED; PG8_LDA(At, 0, 0); PG8_STAGE(PG8_SA(1, 1), a1 + hstepA, voffA);
;             PG8_WAIT_V(8); PG8_WAIT_L(0); PG8_BAR; PG8_MMA(0, 0, At, B0); PG8_MMA(0, 1, At, B1); PG8_BAR; PG8_SCHED;
;             PG8_LDA(At, 0, 1); PG8_STAGE(PG8_SB(0, 0), b2, voffB); PG8_STAGE(PG8_SB(0, 1), b2 + hstepB, voffB); PG8_STAGE(PG8_SA(0, 0), a2, voffA);
;             PG8_WAIT_V(8); PG8_WAIT_L(0); PG8_BAR; PG8_MMA(1, 0, At, B0); PG8_MMA(1, 1, At, B1); PG8_BAR; PG8_SCHED;
.LBB0_968:
	s_add_u32 s56, s54, 0x100
	s_addc_u32 s57, s55, 0
	s_add_i32 s62, 0, 0x10000
	s_cmp_eq_u32 s93, 28
	s_cselect_b32 s49, s41, s57
	s_cselect_b32 s48, s42, s56
	s_cselect_b32 vcc_hi, s43, s61
	s_cselect_b32 vcc_lo, s59, s60
	s_add_i32 s63, 0, 0x14000
	v_add_u32_e32 v116, s62, v228
	v_add_u32_e32 v132, s63, v228
	s_mov_b32 m0, s94
	s_add_u32 s100, s54, 0x80
	s_addc_u32 s101, s55, 0
	global_load_lds_dwordx4 v176, s[100:101]
	s_mov_b32 m0, s95
	ds_read_b128 v[104:107], v116
	ds_read_b128 v[108:111], v116 offset:1024
	ds_read_b128 v[112:115], v116 offset:2048
	ds_read_b128 v[116:119], v116 offset:3072
	global_load_lds_dwordx4 v174, s[100:101]
	ds_read_b128 v[120:123], v132
	ds_read_b128 v[124:127], v132 offset:1024
	ds_read_b128 v[128:131], v132 offset:2048
	ds_read_b128 v[132:135], v132 offset:3072
	s_add_i32 m0, s79, 0xc000
	s_add_u32 s100, s100, 0x80000
	s_addc_u32 s101, s101, 0
	global_load_lds_dwordx4 v176, s[100:101]
	s_add_i32 m0, s79, 0xe000
	ds_read_b128 v[144:147], v231
	ds_read_b128 v[164:167], v231 offset:1024
	ds_read_b128 v[168:171], v231 offset:2048
	ds_read_b128 v[186:189], v231 offset:3072
	global_load_lds_dwordx4 v174, s[100:101]
	ds_read_b128 v[200:203], v231 offset:4096
	ds_read_b128 v[204:207], v231 offset:5120
	ds_read_b128 v[208:211], v231 offset:6144
	ds_read_b128 v[212:215], v231 offset:7168
	s_waitcnt vmcnt(8)
	s_waitcnt lgkmcnt(4)
	s_barrier
	s_setprio 1
	v_mfma_f32_16x16x32_bf16 v[160:163], v[104:107], v[144:147], v[160:163]
	v_mfma_f32_16x16x32_bf16 v[60:63], v[112:115], v[144:147], v[60:63]
	v_mfma_f32_16x16x32_bf16 v[152:155], v[104:107], v[168:171], v[152:155]
	v_mfma_f32_16x16x32_bf16 v[36:39], v[112:115], v[168:171], v[36:39]
	s_waitcnt lgkmcnt(0)
	v_mfma_f32_16x16x32_bf16 v[140:143], v[104:107], v[200:203], v[140:143]
	v_mfma_f32_16x16x32_bf16 v[56:59], v[112:115], v[200:203], v[56:59]
	v_mfma_f32_16x16x32_bf16 v[100:103], v[104:107], v[208:211], v[100:103]
	v_mfma_f32_16x16x32_bf16 v[48:51], v[112:115], v[208:211], v[48:51]
	v_mfma_f32_16x16x32_bf16 v[160:163], v[108:111], v[164:167], v[160:163]
	v_mfma_f32_16x16x32_bf16 v[60:63], v[116:119], v[164:167], v[60:63]
	v_mfma_f32_16x16x32_bf16 v[152:155], v[108:111], v[186:189], v[152:155]
	v_mfma_f32_16x16x32_bf16 v[36:39], v[116:119], v[186:189], v[36:39]
	v_mfma_f32_16x16x32_bf16 v[140:143], v[108:111], v[204:207], v[140:143]
	v_mfma_f32_16x16x32_bf16 v[56:59], v[116:119], v[204:207], v[56:59]
	v_mfma_f32_16x16x32_bf16 v[100:103], v[108:111], v[212:215], v[100:103]
	v_mfma_f32_16x16x32_bf16 v[48:51], v[116:119], v[212:215], v[48:51]
	s_setprio 0
	s_setprio 1
	v_mfma_f32_16x16x32_bf16 v[156:159], v[120:123], v[144:147], v[156:159]
	v_mfma_f32_16x16x32_bf16 v[52:55], v[128:131], v[144:147], v[52:55]
	v_mfma_f32_16x16x32_bf16 v[32:35], v[128:131], v[168:171], v[32:35]
	v_mfma_f32_16x16x32_bf16 v[136:139], v[120:123], v[200:203], v[136:139]
	v_mfma_f32_16x16x32_bf16 v[44:47], v[128:131], v[200:203], v[44:47]
	v_mfma_f32_16x16x32_bf16 v[96:99], v[120:123], v[208:211], v[96:99]
	v_mfma_f32_16x16x32_bf16 v[40:43], v[128:131], v[208:211], v[40:43]
	v_mfma_f32_16x16x32_bf16 v[156:159], v[124:127], v[164:167], v[156:159]
	v_mfma_f32_16x16x32_bf16 v[52:55], v[132:135], v[164:167], v[52:55]
	v_mfma_f32_16x16x32_bf16 v[144:147], v[120:123], v[168:171], v[148:151]
	v_mfma_f32_16x16x32_bf16 v[32:35], v[132:135], v[186:189], v[32:35]
	v_mfma_f32_16x16x32_bf16 v[136:139], v[124:127], v[204:207], v[136:139]
	v_mfma_f32_16x16x32_bf16 v[44:47], v[132:135], v[204:207], v[44:47]
	v_mfma_f32_16x16x32_bf16 v[96:99], v[124:127], v[212:215], v[96:99]
	v_mfma_f32_16x16x32_bf16 v[40:43], v[132:135], v[212:215], v[40:43]
	v_mfma_f32_16x16x32_bf16 v[144:147], v[124:127], v[186:189], v[144:147]
	s_setprio 0
	s_barrier
	s_add_i32 s54, s62, s89
	s_mov_b32 m0, s54
	s_mov_b64 s[100:101], vcc
	global_load_lds_dwordx4 v192, s[100:101]
	s_add_i32 m0, s54, 0x2000
	ds_read_b128 v[148:151], v231 offset:16384
	ds_read_b128 v[164:167], v231 offset:17408
	s_add_u32 s54, vcc_lo, 0x80000
	s_addc_u32 s55, vcc_hi, 0
	s_add_i32 s62, s63, s89
	global_load_lds_dwordx4 v172, s[100:101]
	s_mov_b32 m0, s62
	ds_read_b128 v[168:171], v231 offset:18432
	ds_read_b128 v[186:189], v231 offset:19456
	global_load_lds_dwordx4 v192, s[54:55]
	s_add_i32 m0, s62, 0x2000
	ds_read_b128 v[200:203], v231 offset:20480
	ds_read_b128 v[204:207], v231 offset:21504
	global_load_lds_dwordx4 v172, s[54:55]
	ds_read_b128 v[208:211], v231 offset:22528
	ds_read_b128 v[212:215], v231 offset:23552
	s_waitcnt vmcnt(6)
	s_waitcnt lgkmcnt(0)
	s_barrier
; #define PG8_STAGE(bufoff, gbase, voff) do { _Pragma("unroll") for (int _i = 0; _i < 2; ++_i) \
;         __builtin_amdgcn_global_load_lds((const unsigned*)((const char*)(gbase) + (voff)[_i]), (LAS unsigned*)(lds + (bufoff) + ldsw + _i * 8192), 16, 0, 0); } while (0)
; #define PG8_LDA(dst, b, h) do { _Pragma("unroll") for (int m = 0; m < 4; ++m) _Pragma("unroll") for (int k = 0; k < 2; ++k) dst[m][k] = *(const LAS bf16x8*)(lds + PG8_SA(b, h) + aoff + m * 2048 + k * 1024); } while (0)
; #define PG8_LDB(dst, b, h) do { _Pragma("unroll") for (int n = 0; n < 2; ++n) _Pragma("unroll") for (int k = 0; k < 2; ++k) dst[n][k] = *(const LAS bf16x8*)(lds + PG8_SB(b, h) + boff + n * 2048 + k * 1024); } while (0)
; #define PG8_MMA(ai, bj, At, Bt) do { __builtin_amdgcn_s_setprio(1); _Pragma("unroll") for (int m = 0; m < 4; ++m) _Pragma("unroll") for (int n = 0; n < 2; ++n) _Pragma("unroll") for (int k = 0; k < 2; ++k) \
;         acc[ai][bj][m][n] = __builtin_amdgcn_mfma_f32_16x16x32_bf16(Bt[n][k], At[m][k], acc[ai][bj][m][n], 0, 0, 0); __builtin_amdgcn_s_setprio(0); } while (0)
; #define PG8_WAIT_V(n) asm volatile("s_waitcnt vmcnt(" #n ")" ::: "memory")
; #define PG8_WAIT_L(n) asm volatile("s_waitcnt lgkmcnt(" #n ")" ::: "memory")
; #define PG8_BAR __builtin_amdgcn_s_barrier()
; #define PG8_SCHED __builtin_amdgcn_sched_barrier(0)
; template <class Epi, class Sched, bool ALIGN_EPI = false, bool SP2 = false>
; __device__ __forceinline__ void gemm_phase(LAS unsigned char* lds, const Gemm g, const Sched& S, const Epi& E, int wid) {
;     ...
;             PG8_WAIT_V(8); PG8_WAIT_L(0); PG8_BAR; PG8_MMA(0, 0, At, B0); PG8_MMA(0, 1, At, B1); PG8_BAR; PG8_SCHED;
;             PG8_LDA(At, 0, 1); PG8_STAGE(PG8_SB(0, 0), b2, voffB); PG8_STAGE(PG8_SB(0, 1), b2 + hstepB, voffB); PG8_STAGE(PG8_SA(0, 0), a2, voffA);
;             PG8_WAIT_V(8); PG8_WAIT_L(0); PG8_BAR; PG8_MMA(1, 0, At, B0); PG8_MMA(1, 1, At, B1); PG8_BAR; PG8_SCHED;
;             PG8_LDB(B0, 1, 0); PG8_LDB(B1, 1, 1); PG8_SCHED; PG8_LDA(At, 1, 0); PG8_STAGE(PG8_SA(0, 1), a2 + hstepA, voffA);
;             PG8_WAIT_V(8); PG8_WAIT_L(0); PG8_BAR; PG8_MMA(0, 0, At, B0); PG8_MMA(0, 1, At, B1); PG8_BAR; PG8_SCHED;
;             PG8_LDA(At, 1, 1); PG8_STAGE(PG8_SB(1, 0), b3, voffB); PG8_STAGE(PG8_SB(1, 1), b3 + hstepB, voffB); PG8_STAGE(PG8_SA(1, 0), a3, voffA);
	s_setprio 1
	s_waitcnt lgkmcnt(0)
	v_mfma_f32_16x16x32_bf16 v[92:95], v[104:107], v[148:151], v[92:95]
	v_mfma_f32_16x16x32_bf16 v[28:31], v[112:115], v[148:151], v[28:31]
	v_mfma_f32_16x16x32_bf16 v[88:91], v[104:107], v[168:171], v[88:91]
	v_mfma_f32_16x16x32_bf16 v[4:7], v[112:115], v[168:171], v[4:7]
	v_mfma_f32_16x16x32_bf16 v[80:83], v[104:107], v[200:203], v[80:83]
	v_mfma_f32_16x16x32_bf16 v[24:27], v[112:115], v[200:203], v[24:27]
	v_mfma_f32_16x16x32_bf16 v[72:75], v[104:107], v[208:211], v[72:75]
	v_mfma_f32_16x16x32_bf16 v[16:19], v[112:115], v[208:211], v[16:19]
	v_mfma_f32_16x16x32_bf16 v[92:95], v[108:111], v[164:167], v[92:95]
	v_mfma_f32_16x16x32_bf16 v[28:31], v[116:119], v[164:167], v[28:31]
	v_mfma_f32_16x16x32_bf16 v[88:91], v[108:111], v[186:189], v[88:91]
	v_mfma_f32_16x16x32_bf16 v[4:7], v[116:119], v[186:189], v[4:7]
	v_mfma_f32_16x16x32_bf16 v[80:83], v[108:111], v[204:207], v[80:83]
	v_mfma_f32_16x16x32_bf16 v[24:27], v[116:119], v[204:207], v[24:27]
	v_mfma_f32_16x16x32_bf16 v[72:75], v[108:111], v[212:215], v[72:75]
	v_mfma_f32_16x16x32_bf16 v[16:19], v[116:119], v[212:215], v[16:19]
	s_setprio 0
	s_setprio 1
	v_mfma_f32_16x16x32_bf16 v[84:87], v[120:123], v[148:151], v[84:87]
	v_mfma_f32_16x16x32_bf16 v[20:23], v[128:131], v[148:151], v[20:23]
	v_mfma_f32_16x16x32_bf16 v[76:79], v[120:123], v[168:171], v[76:79]
	v_mfma_f32_16x16x32_bf16 v[0:3], v[128:131], v[168:171], v[0:3]
	v_mfma_f32_16x16x32_bf16 v[68:71], v[120:123], v[200:203], v[68:71]
	v_mfma_f32_16x16x32_bf16 v[12:15], v[128:131], v[200:203], v[12:15]
	v_mfma_f32_16x16x32_bf16 v[64:67], v[120:123], v[208:211], v[64:67]
	v_mfma_f32_16x16x32_bf16 v[8:11], v[128:131], v[208:211], v[8:11]
	v_mfma_f32_16x16x32_bf16 v[84:87], v[124:127], v[164:167], v[84:87]
	v_mfma_f32_16x16x32_bf16 v[20:23], v[132:135], v[164:167], v[20:23]
	v_mfma_f32_16x16x32_bf16 v[76:79], v[124:127], v[186:189], v[76:79]
	v_mfma_f32_16x16x32_bf16 v[0:3], v[132:135], v[186:189], v[0:3]
	v_mfma_f32_16x16x32_bf16 v[68:71], v[124:127], v[204:207], v[68:71]
	v_mfma_f32_16x16x32_bf16 v[12:15], v[132:135], v[204:207], v[12:15]
	v_mfma_f32_16x16x32_bf16 v[64:67], v[124:127], v[212:215], v[64:67]
	v_mfma_f32_16x16x32_bf16 v[8:11], v[132:135], v[212:215], v[8:11]
	s_setprio 0
	s_barrier
	s_add_i32 s54, 0, 0x18000
	s_add_i32 s55, 0, 0x1c000
	v_add_u32_e32 v116, s54, v228
	v_add_u32_e32 v132, s55, v228
	s_add_u32 s48, s48, 0x80000
	s_addc_u32 s49, s49, 0
	s_mov_b32 m0, s79
	s_add_u32 s100, s48, 0xfff80000
	s_addc_u32 s101, s49, -1
	global_load_lds_dwordx4 v176, s[100:101]
	s_mov_b32 m0, s81
	ds_read_b128 v[104:107], v116
	ds_read_b128 v[108:111], v116 offset:1024
	ds_read_b128 v[112:115], v116 offset:2048
	ds_read_b128 v[116:119], v116 offset:3072
	global_load_lds_dwordx4 v174, s[100:101]
	s_mov_b32 m0, s77
	ds_read_b128 v[120:123], v132
	ds_read_b128 v[124:127], v132 offset:1024
	ds_read_b128 v[128:131], v132 offset:2048
	ds_read_b128 v[132:135], v132 offset:3072
	global_load_lds_dwordx4 v176, s[48:49]
	s_mov_b32 m0, s4
	ds_read_b128 v[148:151], v231 offset:32768
	ds_read_b128 v[164:167], v231 offset:33792
	ds_read_b128 v[168:171], v231 offset:34816
	ds_read_b128 v[186:189], v231 offset:35840
	global_load_lds_dwordx4 v174, s[48:49]
	ds_read_b128 v[200:203], v231 offset:36864
	ds_read_b128 v[204:207], v231 offset:37888
	ds_read_b128 v[208:211], v231 offset:38912
	ds_read_b128 v[212:215], v231 offset:39936
	s_waitcnt vmcnt(8)
	s_waitcnt lgkmcnt(4)
	s_barrier
; #define PG8_STAGE(bufoff, gbase, voff) do { _Pragma("unroll") for (int _i = 0; _i < 2; ++_i) \
;         __builtin_amdgcn_global_load_lds((const unsigned*)((const char*)(gbase) + (voff)[_i]), (LAS unsigned*)(lds + (bufoff) + ldsw + _i * 8192), 16, 0, 0); } while (0)
; #define PG8_LDA(dst, b, h) do { _Pragma("unroll") for (int m = 0; m < 4; ++m) _Pragma("unroll") for (int k = 0; k < 2; ++k) dst[m][k] = *(const LAS bf16x8*)(lds + PG8_SA(b, h) + aoff + m * 2048 + k * 1024); } while (0)
; #define PG8_LDB(dst, b, h) do { _Pragma("unroll") for (int n = 0; n < 2; ++n) _Pragma("unroll") for (int k = 0; k < 2; ++k) dst[n][k] = *(const LAS bf16x8*)(lds + PG8_SB(b, h) + boff + n * 2048 + k * 1024); } while (0)
; #define PG8_MMA(ai, bj, At, Bt) do { __builtin_amdgcn_s_setprio(1); _Pragma("unroll") for (int m = 0; m < 4; ++m) _Pragma("unroll") for (int n = 0; n < 2; ++n) _Pragma("unroll") for (int k = 0; k < 2; ++k) \
;         acc[ai][bj][m][n] = __builtin_amdgcn_mfma_f32_16x16x32_bf16(Bt[n][k], At[m][k], acc[ai][bj][m][n], 0, 0, 0); __builtin_amdgcn_s_setprio(0); } while (0)
; #define PG8_WAIT_V(n) asm volatile("s_waitcnt vmcnt(" #n ")" ::: "memory")
; #define PG8_WAIT_L(n) asm volatile("s_waitcnt lgkmcnt(" #n ")" ::: "memory")
; #define PG8_BAR __builtin_amdgcn_s_barrier()
; #define PG8_SCHED __builtin_amdgcn_sched_barrier(0)
; template <class Epi, class Sched, bool ALIGN_EPI = false, bool SP2 = false>
; __device__ __forceinline__ void gemm_phase(LAS unsigned char* lds, const Gemm g, const Sched& S, const Epi& E, int wid) {
;     ...
;             PG8_LDB(B0, 1, 0); PG8_LDB(B1, 1, 1); PG8_SCHED; PG8_LDA(At, 1, 0); PG8_STAGE(PG8_SA(0, 1), a2 + hstepA, voffA);
;             PG8_WAIT_V(8); PG8_WAIT_L(0); PG8_BAR; PG8_MMA(0, 0, At, B0); PG8_MMA(0, 1, At, B1); PG8_BAR; PG8_SCHED;
;             PG8_LDA(At, 1, 1); PG8_STAGE(PG8_SB(1, 0), b3, voffB); PG8_STAGE(PG8_SB(1, 1), b3 + hstepB, voffB); PG8_STAGE(PG8_SA(1, 0), a3, voffA);
;             PG8_WAIT_V(8); PG8_WAIT_L(0); PG8_BAR; PG8_MMA(1, 0, At, B0); PG8_MMA(1, 1, At, B1); PG8_BAR; PG8_SCHED;
	s_setprio 1
	v_mfma_f32_16x16x32_bf16 v[160:163], v[104:107], v[148:151], v[160:163]
	v_mfma_f32_16x16x32_bf16 v[60:63], v[112:115], v[148:151], v[60:63]
	v_mfma_f32_16x16x32_bf16 v[152:155], v[104:107], v[168:171], v[152:155]
	v_mfma_f32_16x16x32_bf16 v[36:39], v[112:115], v[168:171], v[36:39]
	s_waitcnt lgkmcnt(0)
	v_mfma_f32_16x16x32_bf16 v[140:143], v[104:107], v[200:203], v[140:143]
	v_mfma_f32_16x16x32_bf16 v[56:59], v[112:115], v[200:203], v[56:59]
	v_mfma_f32_16x16x32_bf16 v[100:103], v[104:107], v[208:211], v[100:103]
	v_mfma_f32_16x16x32_bf16 v[48:51], v[112:115], v[208:211], v[48:51]
	v_mfma_f32_16x16x32_bf16 v[160:163], v[108:111], v[164:167], v[160:163]
	v_mfma_f32_16x16x32_bf16 v[60:63], v[116:119], v[164:167], v[60:63]
	v_mfma_f32_16x16x32_bf16 v[152:155], v[108:111], v[186:189], v[152:155]
	v_mfma_f32_16x16x32_bf16 v[36:39], v[116:119], v[186:189], v[36:39]
	v_mfma_f32_16x16x32_bf16 v[140:143], v[108:111], v[204:207], v[140:143]
	v_mfma_f32_16x16x32_bf16 v[56:59], v[116:119], v[204:207], v[56:59]
	v_mfma_f32_16x16x32_bf16 v[100:103], v[108:111], v[212:215], v[100:103]
	v_mfma_f32_16x16x32_bf16 v[48:51], v[116:119], v[212:215], v[48:51]
	s_setprio 0
	s_setprio 1
	v_mfma_f32_16x16x32_bf16 v[156:159], v[120:123], v[148:151], v[156:159]
	v_mfma_f32_16x16x32_bf16 v[52:55], v[128:131], v[148:151], v[52:55]
	v_mfma_f32_16x16x32_bf16 v[144:147], v[120:123], v[168:171], v[144:147]
	v_mfma_f32_16x16x32_bf16 v[32:35], v[128:131], v[168:171], v[32:35]
	v_mfma_f32_16x16x32_bf16 v[136:139], v[120:123], v[200:203], v[136:139]
	v_mfma_f32_16x16x32_bf16 v[44:47], v[128:131], v[200:203], v[44:47]
	v_mfma_f32_16x16x32_bf16 v[96:99], v[120:123], v[208:211], v[96:99]
	v_mfma_f32_16x16x32_bf16 v[40:43], v[128:131], v[208:211], v[40:43]
	v_mfma_f32_16x16x32_bf16 v[156:159], v[124:127], v[164:167], v[156:159]
	v_mfma_f32_16x16x32_bf16 v[52:55], v[132:135], v[164:167], v[52:55]
	v_mfma_f32_16x16x32_bf16 v[148:151], v[124:127], v[186:189], v[144:147]
	v_mfma_f32_16x16x32_bf16 v[32:35], v[132:135], v[186:189], v[32:35]
	v_mfma_f32_16x16x32_bf16 v[136:139], v[124:127], v[204:207], v[136:139]
	v_mfma_f32_16x16x32_bf16 v[44:47], v[132:135], v[204:207], v[44:47]
	v_mfma_f32_16x16x32_bf16 v[96:99], v[124:127], v[212:215], v[96:99]
	v_mfma_f32_16x16x32_bf16 v[40:43], v[132:135], v[212:215], v[40:43]
	s_setprio 0
	s_barrier
	s_add_i32 s48, s54, s89
	s_mov_b32 m0, s48
	s_add_u32 s100, vcc_lo, 0x80
	s_addc_u32 s101, vcc_hi, 0
	global_load_lds_dwordx4 v192, s[100:101]
	s_add_i32 m0, s48, 0x2000
	ds_read_b128 v[144:147], v231 offset:49152
	ds_read_b128 v[164:167], v231 offset:50176
	s_add_u32 s48, vcc_lo, 0x80080
	s_addc_u32 s49, vcc_hi, 0
	s_add_i32 s54, s55, s89
	global_load_lds_dwordx4 v172, s[100:101]
	s_mov_b32 m0, s54
	ds_read_b128 v[168:171], v231 offset:51200
	ds_read_b128 v[186:189], v231 offset:52224
	global_load_lds_dwordx4 v192, s[48:49]
	s_add_i32 m0, s54, 0x2000
	ds_read_b128 v[200:203], v231 offset:53248
	ds_read_b128 v[204:207], v231 offset:54272
	global_load_lds_dwordx4 v172, s[48:49]
	ds_read_b128 v[208:211], v231 offset:55296
	ds_read_b128 v[212:215], v231 offset:56320
	s_waitcnt vmcnt(6)
	s_waitcnt lgkmcnt(0)
	s_barrier
	s_setprio 1
	s_waitcnt lgkmcnt(0)
	v_mfma_f32_16x16x32_bf16 v[92:95], v[104:107], v[144:147], v[92:95]
	v_mfma_f32_16x16x32_bf16 v[28:31], v[112:115], v[144:147], v[28:31]
	v_mfma_f32_16x16x32_bf16 v[88:91], v[104:107], v[168:171], v[88:91]
	v_mfma_f32_16x16x32_bf16 v[4:7], v[112:115], v[168:171], v[4:7]
	v_mfma_f32_16x16x32_bf16 v[80:83], v[104:107], v[200:203], v[80:83]
	v_mfma_f32_16x16x32_bf16 v[24:27], v[112:115], v[200:203], v[24:27]
	v_mfma_f32_16x16x32_bf16 v[72:75], v[104:107], v[208:211], v[72:75]
	v_mfma_f32_16x16x32_bf16 v[16:19], v[112:115], v[208:211], v[16:19]
	v_mfma_f32_16x16x32_bf16 v[92:95], v[108:111], v[164:167], v[92:95]
	v_mfma_f32_16x16x32_bf16 v[28:31], v[116:119], v[164:167], v[28:31]
	v_mfma_f32_16x16x32_bf16 v[88:91], v[108:111], v[186:189], v[88:91]
	v_mfma_f32_16x16x32_bf16 v[4:7], v[116:119], v[186:189], v[4:7]
	v_mfma_f32_16x16x32_bf16 v[80:83], v[108:111], v[204:207], v[80:83]
	v_mfma_f32_16x16x32_bf16 v[24:27], v[116:119], v[204:207], v[24:27]
	v_mfma_f32_16x16x32_bf16 v[72:75], v[108:111], v[212:215], v[72:75]
	v_mfma_f32_16x16x32_bf16 v[16:19], v[116:119], v[212:215], v[16:19]
	s_setprio 0
	s_setprio 1
	v_mfma_f32_16x16x32_bf16 v[84:87], v[120:123], v[144:147], v[84:87]
	v_mfma_f32_16x16x32_bf16 v[20:23], v[128:131], v[144:147], v[20:23]
	v_mfma_f32_16x16x32_bf16 v[76:79], v[120:123], v[168:171], v[76:79]
	v_mfma_f32_16x16x32_bf16 v[0:3], v[128:131], v[168:171], v[0:3]
	v_mfma_f32_16x16x32_bf16 v[68:71], v[120:123], v[200:203], v[68:71]
	v_mfma_f32_16x16x32_bf16 v[12:15], v[128:131], v[200:203], v[12:15]
	v_mfma_f32_16x16x32_bf16 v[64:67], v[120:123], v[208:211], v[64:67]
	v_mfma_f32_16x16x32_bf16 v[8:11], v[128:131], v[208:211], v[8:11]
	v_mfma_f32_16x16x32_bf16 v[84:87], v[124:127], v[164:167], v[84:87]
	v_mfma_f32_16x16x32_bf16 v[20:23], v[132:135], v[164:167], v[20:23]
	v_mfma_f32_16x16x32_bf16 v[76:79], v[124:127], v[186:189], v[76:79]
	v_mfma_f32_16x16x32_bf16 v[0:3], v[132:135], v[186:189], v[0:3]
	v_mfma_f32_16x16x32_bf16 v[68:71], v[124:127], v[204:207], v[68:71]
	v_mfma_f32_16x16x32_bf16 v[12:15], v[132:135], v[204:207], v[12:15]
	v_mfma_f32_16x16x32_bf16 v[64:67], v[124:127], v[212:215], v[64:67]
	v_mfma_f32_16x16x32_bf16 v[8:11], v[132:135], v[212:215], v[8:11]
	s_setprio 0
	s_barrier
	s_add_i32 s93, s93, 2
	s_add_u32 s60, s60, 0x100
	s_addc_u32 s61, s61, 0
	s_cmp_gt_u32 s93, 29
	s_mov_b64 s[54:55], s[56:57]
	s_cbranch_scc0 .LBB0_968
	s_and_b64 vcc, exec, s[82:83]
	s_cbranch_vccz .LBB0_971
	s_barrier
